# all s_setprio flips removed from the GEMM K-loops (two waves per SIMD alternate MFMA / load phases by barrier; the per-phase priority raise cost time here)
# speedup vs baseline: 1.0246x; 1.0153x over previous
.LBB0_281:
	v_add_u32_e32 v145, s59, v165
	ds_read_b128 v[132:135], v145
	ds_read_b128 v[156:159], v145 offset:1024
	ds_read_b128 v[160:163], v145 offset:2048
	ds_read_b128 v[170:173], v145 offset:3072
	s_add_u32 s22, s21, s0
	s_addc_u32 s38, s40, s1
	s_and_b64 s[36:37], exec, s[36:37]
	s_cselect_b32 s37, s13, s38
	s_cselect_b32 s36, s19, s22
	v_lshl_add_u64 v[208:209], v[128:129], 0, s[0:1]
	s_add_i32 m0, s44, 0xc000
	ds_read_b128 v[174:177], v167
	ds_read_b128 v[178:181], v167 offset:1024
	ds_read_b128 v[182:185], v167 offset:2048
	ds_read_b128 v[186:189], v167 offset:3072
	ds_read_b128 v[190:193], v167 offset:4096
	ds_read_b128 v[196:199], v167 offset:5120
	ds_read_b128 v[200:203], v167 offset:6144
	ds_read_b128 v[204:207], v167 offset:7168
	global_load_lds_dwordx4 v[208:209], off
	v_lshl_add_u64 v[208:209], v[130:131], 0, s[0:1]
	s_add_i32 m0, s44, 0xe000
	s_nop 0
	global_load_lds_dwordx4 v[208:209], off
	s_waitcnt lgkmcnt(8)
	s_barrier
	s_waitcnt lgkmcnt(0)
	s_waitcnt lgkmcnt(0)
	v_mfma_f32_16x16x32_bf16 v[60:63], v[132:135], v[174:177], v[60:63]
	v_mfma_f32_16x16x32_bf16 v[56:59], v[160:163], v[174:177], v[56:59]
	v_mfma_f32_16x16x32_bf16 v[52:55], v[132:135], v[182:185], v[52:55]
	v_mfma_f32_16x16x32_bf16 v[48:51], v[160:163], v[182:185], v[48:51]
	v_mfma_f32_16x16x32_bf16 v[44:47], v[132:135], v[190:193], v[44:47]
	v_mfma_f32_16x16x32_bf16 v[40:43], v[160:163], v[190:193], v[40:43]
	v_mfma_f32_16x16x32_bf16 v[36:39], v[132:135], v[200:203], v[36:39]
	v_mfma_f32_16x16x32_bf16 v[32:35], v[160:163], v[200:203], v[32:35]
	v_mfma_f32_16x16x32_bf16 v[60:63], v[156:159], v[178:181], v[60:63]
	v_mfma_f32_16x16x32_bf16 v[56:59], v[170:173], v[178:181], v[56:59]
	v_mfma_f32_16x16x32_bf16 v[52:55], v[156:159], v[186:189], v[52:55]
	v_mfma_f32_16x16x32_bf16 v[48:51], v[170:173], v[186:189], v[48:51]
	v_mfma_f32_16x16x32_bf16 v[44:47], v[156:159], v[196:199], v[44:47]
	v_mfma_f32_16x16x32_bf16 v[40:43], v[170:173], v[196:199], v[40:43]
	v_mfma_f32_16x16x32_bf16 v[36:39], v[156:159], v[204:207], v[36:39]
	v_mfma_f32_16x16x32_bf16 v[32:35], v[170:173], v[204:207], v[32:35]
	s_barrier
	s_add_i32 s22, s59, s43
	v_add_u32_e32 v145, s63, v165
	v_lshl_add_u64 v[224:225], s[36:37], 0, v[138:139]
	s_mov_b32 m0, s22
	ds_read_b128 v[208:211], v145
	ds_read_b128 v[212:215], v145 offset:1024
	ds_read_b128 v[216:219], v145 offset:2048
	ds_read_b128 v[220:223], v145 offset:3072
	global_load_lds_dwordx4 v[224:225], off
	v_lshl_add_u64 v[226:227], s[36:37], 0, v[142:143]
	s_add_i32 m0, s22, 0x2000
	s_nop 0
	global_load_lds_dwordx4 v[226:227], off
	s_barrier
	s_waitcnt lgkmcnt(0)
	s_waitcnt lgkmcnt(0)
	v_mfma_f32_16x16x32_bf16 v[124:127], v[208:211], v[174:177], v[124:127]
	v_mfma_f32_16x16x32_bf16 v[120:123], v[216:219], v[174:177], v[120:123]
	v_mfma_f32_16x16x32_bf16 v[116:119], v[208:211], v[182:185], v[116:119]
	v_mfma_f32_16x16x32_bf16 v[112:115], v[216:219], v[182:185], v[112:115]
	v_mfma_f32_16x16x32_bf16 v[108:111], v[208:211], v[190:193], v[108:111]
	v_mfma_f32_16x16x32_bf16 v[104:107], v[216:219], v[190:193], v[104:107]
	v_mfma_f32_16x16x32_bf16 v[100:103], v[208:211], v[200:203], v[100:103]
	v_mfma_f32_16x16x32_bf16 v[96:99], v[216:219], v[200:203], v[96:99]
	v_mfma_f32_16x16x32_bf16 v[124:127], v[212:215], v[178:181], v[124:127]
	v_mfma_f32_16x16x32_bf16 v[120:123], v[220:223], v[178:181], v[120:123]
	v_mfma_f32_16x16x32_bf16 v[116:119], v[212:215], v[186:189], v[116:119]
	v_mfma_f32_16x16x32_bf16 v[112:115], v[220:223], v[186:189], v[112:115]
	v_mfma_f32_16x16x32_bf16 v[108:111], v[212:215], v[196:199], v[108:111]
	v_mfma_f32_16x16x32_bf16 v[104:107], v[220:223], v[196:199], v[104:107]
	v_mfma_f32_16x16x32_bf16 v[100:103], v[212:215], v[204:207], v[100:103]
	v_mfma_f32_16x16x32_bf16 v[96:99], v[220:223], v[204:207], v[96:99]
	s_mov_b32 m0, s44
	v_lshl_add_u64 v[228:229], s[10:11], 0, v[136:137]
	s_barrier
	ds_read_b128 v[174:177], v167 offset:16384
	ds_read_b128 v[178:181], v167 offset:17408
	ds_read_b128 v[182:185], v167 offset:18432
	ds_read_b128 v[186:189], v167 offset:19456
	ds_read_b128 v[190:193], v167 offset:20480
	ds_read_b128 v[196:199], v167 offset:21504
	ds_read_b128 v[200:203], v167 offset:22528
	ds_read_b128 v[204:207], v167 offset:23552
	global_load_lds_dwordx4 v[228:229], off
	v_lshl_add_u64 v[230:231], s[10:11], 0, v[140:141]
	s_mov_b32 m0, s45
	s_nop 0
	global_load_lds_dwordx4 v[230:231], off
	s_barrier
	s_waitcnt lgkmcnt(0)
	s_waitcnt lgkmcnt(0)
	v_mfma_f32_16x16x32_bf16 v[28:31], v[132:135], v[174:177], v[28:31]
	v_mfma_f32_16x16x32_bf16 v[24:27], v[160:163], v[174:177], v[24:27]
	v_mfma_f32_16x16x32_bf16 v[20:23], v[132:135], v[182:185], v[20:23]
	v_mfma_f32_16x16x32_bf16 v[16:19], v[160:163], v[182:185], v[16:19]
	v_mfma_f32_16x16x32_bf16 v[12:15], v[132:135], v[190:193], v[12:15]
	v_mfma_f32_16x16x32_bf16 v[8:11], v[160:163], v[190:193], v[8:11]
	v_mfma_f32_16x16x32_bf16 v[4:7], v[132:135], v[200:203], v[4:7]
	v_mfma_f32_16x16x32_bf16 v[0:3], v[160:163], v[200:203], v[0:3]
	v_mfma_f32_16x16x32_bf16 v[28:31], v[156:159], v[178:181], v[28:31]
	v_mfma_f32_16x16x32_bf16 v[24:27], v[170:173], v[178:181], v[24:27]
	v_mfma_f32_16x16x32_bf16 v[20:23], v[156:159], v[186:189], v[20:23]
	v_mfma_f32_16x16x32_bf16 v[16:19], v[170:173], v[186:189], v[16:19]
	v_mfma_f32_16x16x32_bf16 v[12:15], v[156:159], v[196:199], v[12:15]
	v_mfma_f32_16x16x32_bf16 v[8:11], v[170:173], v[196:199], v[8:11]
	v_mfma_f32_16x16x32_bf16 v[4:7], v[156:159], v[204:207], v[4:7]
	v_mfma_f32_16x16x32_bf16 v[0:3], v[170:173], v[204:207], v[0:3]
	s_barrier
	s_add_u32 s38, s36, 0x40000
	s_addc_u32 s39, s37, 0
	s_add_i32 s22, s63, s43
	v_lshl_add_u64 v[132:133], s[38:39], 0, v[138:139]
	s_mov_b32 m0, s22
	s_nop 0
	global_load_lds_dwordx4 v[132:133], off
	v_lshl_add_u64 v[132:133], s[38:39], 0, v[142:143]
	s_add_i32 m0, s22, 0x2000
	s_nop 0
	global_load_lds_dwordx4 v[132:133], off
	s_waitcnt vmcnt(6)
	s_barrier
	v_mfma_f32_16x16x32_bf16 v[92:95], v[208:211], v[174:177], v[92:95]
	v_mfma_f32_16x16x32_bf16 v[88:91], v[216:219], v[174:177], v[88:91]
	v_mfma_f32_16x16x32_bf16 v[84:87], v[208:211], v[182:185], v[84:87]
	v_mfma_f32_16x16x32_bf16 v[80:83], v[216:219], v[182:185], v[80:83]
	v_mfma_f32_16x16x32_bf16 v[76:79], v[208:211], v[190:193], v[76:79]
	v_mfma_f32_16x16x32_bf16 v[72:75], v[216:219], v[190:193], v[72:75]
	v_mfma_f32_16x16x32_bf16 v[68:71], v[208:211], v[200:203], v[68:71]
	v_mfma_f32_16x16x32_bf16 v[64:67], v[216:219], v[200:203], v[64:67]
	v_mfma_f32_16x16x32_bf16 v[92:95], v[212:215], v[178:181], v[92:95]
	v_mfma_f32_16x16x32_bf16 v[88:91], v[220:223], v[178:181], v[88:91]
	v_mfma_f32_16x16x32_bf16 v[84:87], v[212:215], v[186:189], v[84:87]
	v_mfma_f32_16x16x32_bf16 v[80:83], v[220:223], v[186:189], v[80:83]
	v_mfma_f32_16x16x32_bf16 v[76:79], v[212:215], v[196:199], v[76:79]
	v_mfma_f32_16x16x32_bf16 v[72:75], v[220:223], v[196:199], v[72:75]
	v_mfma_f32_16x16x32_bf16 v[68:71], v[212:215], v[204:207], v[68:71]
	v_mfma_f32_16x16x32_bf16 v[64:67], v[220:223], v[204:207], v[64:67]
	s_add_i32 s22, 0, 0x18000
	v_add_u32_e32 v145, s22, v165
	s_barrier
	ds_read_b128 v[132:135], v145
	ds_read_b128 v[156:159], v145 offset:1024
	ds_read_b128 v[160:163], v145 offset:2048
	ds_read_b128 v[170:173], v145 offset:3072
	s_add_u32 s10, s10, 0x40000
	s_addc_u32 s11, s11, 0
	s_mov_b32 m0, s46
	v_lshl_add_u64 v[208:209], s[10:11], 0, v[136:137]
	ds_read_b128 v[174:177], v167 offset:32768
	ds_read_b128 v[178:181], v167 offset:33792
	ds_read_b128 v[182:185], v167 offset:34816
	ds_read_b128 v[186:189], v167 offset:35840
	ds_read_b128 v[190:193], v167 offset:36864
	ds_read_b128 v[196:199], v167 offset:37888
	ds_read_b128 v[200:203], v167 offset:38912
	ds_read_b128 v[204:207], v167 offset:39936
	global_load_lds_dwordx4 v[208:209], off
	v_lshl_add_u64 v[208:209], s[10:11], 0, v[140:141]
	s_mov_b32 m0, s47
	s_nop 0
	global_load_lds_dwordx4 v[208:209], off
	s_waitcnt lgkmcnt(8)
	s_barrier
	s_waitcnt lgkmcnt(0)
	s_waitcnt lgkmcnt(0)
	v_mfma_f32_16x16x32_bf16 v[60:63], v[132:135], v[174:177], v[60:63]
	v_mfma_f32_16x16x32_bf16 v[56:59], v[160:163], v[174:177], v[56:59]
	v_mfma_f32_16x16x32_bf16 v[52:55], v[132:135], v[182:185], v[52:55]
	v_mfma_f32_16x16x32_bf16 v[48:51], v[160:163], v[182:185], v[48:51]
	v_mfma_f32_16x16x32_bf16 v[44:47], v[132:135], v[190:193], v[44:47]
	v_mfma_f32_16x16x32_bf16 v[40:43], v[160:163], v[190:193], v[40:43]
	v_mfma_f32_16x16x32_bf16 v[36:39], v[132:135], v[200:203], v[36:39]
	v_mfma_f32_16x16x32_bf16 v[32:35], v[160:163], v[200:203], v[32:35]
	v_mfma_f32_16x16x32_bf16 v[60:63], v[156:159], v[178:181], v[60:63]
	v_mfma_f32_16x16x32_bf16 v[56:59], v[170:173], v[178:181], v[56:59]
	v_mfma_f32_16x16x32_bf16 v[52:55], v[156:159], v[186:189], v[52:55]
	v_mfma_f32_16x16x32_bf16 v[48:51], v[170:173], v[186:189], v[48:51]
	v_mfma_f32_16x16x32_bf16 v[44:47], v[156:159], v[196:199], v[44:47]
	v_mfma_f32_16x16x32_bf16 v[40:43], v[170:173], v[196:199], v[40:43]
	v_mfma_f32_16x16x32_bf16 v[36:39], v[156:159], v[204:207], v[36:39]
	v_mfma_f32_16x16x32_bf16 v[32:35], v[170:173], v[204:207], v[32:35]
	s_barrier
	s_add_i32 s38, 0, 0x1c000
	s_add_i32 s10, s22, s43
	v_add_u32_e32 v145, s38, v165
	v_lshl_add_u64 v[224:225], v[224:225], 0, s[26:27]
	s_mov_b32 m0, s10
	ds_read_b128 v[208:211], v145
	ds_read_b128 v[212:215], v145 offset:1024
	ds_read_b128 v[216:219], v145 offset:2048
	ds_read_b128 v[220:223], v145 offset:3072
	global_load_lds_dwordx4 v[224:225], off
	v_lshl_add_u64 v[224:225], v[226:227], 0, s[26:27]
	s_add_i32 m0, s10, 0x2000
	s_nop 0
	global_load_lds_dwordx4 v[224:225], off
	s_barrier
	s_waitcnt lgkmcnt(0)
	s_waitcnt lgkmcnt(0)
	v_mfma_f32_16x16x32_bf16 v[124:127], v[208:211], v[174:177], v[124:127]
	v_mfma_f32_16x16x32_bf16 v[120:123], v[216:219], v[174:177], v[120:123]
	v_mfma_f32_16x16x32_bf16 v[116:119], v[208:211], v[182:185], v[116:119]
	v_mfma_f32_16x16x32_bf16 v[112:115], v[216:219], v[182:185], v[112:115]
	v_mfma_f32_16x16x32_bf16 v[108:111], v[208:211], v[190:193], v[108:111]
	v_mfma_f32_16x16x32_bf16 v[104:107], v[216:219], v[190:193], v[104:107]
	v_mfma_f32_16x16x32_bf16 v[100:103], v[208:211], v[200:203], v[100:103]
	v_mfma_f32_16x16x32_bf16 v[96:99], v[216:219], v[200:203], v[96:99]
	v_mfma_f32_16x16x32_bf16 v[124:127], v[212:215], v[178:181], v[124:127]
	v_mfma_f32_16x16x32_bf16 v[120:123], v[220:223], v[178:181], v[120:123]
	v_mfma_f32_16x16x32_bf16 v[116:119], v[212:215], v[186:189], v[116:119]
	v_mfma_f32_16x16x32_bf16 v[112:115], v[220:223], v[186:189], v[112:115]
	v_mfma_f32_16x16x32_bf16 v[108:111], v[212:215], v[196:199], v[108:111]
	v_mfma_f32_16x16x32_bf16 v[104:107], v[220:223], v[196:199], v[104:107]
	v_mfma_f32_16x16x32_bf16 v[100:103], v[212:215], v[204:207], v[100:103]
	v_mfma_f32_16x16x32_bf16 v[96:99], v[220:223], v[204:207], v[96:99]
	s_mov_b32 m0, s48
	v_lshl_add_u64 v[224:225], v[228:229], 0, s[26:27]
	s_barrier
	ds_read_b128 v[174:177], v167 offset:49152
	ds_read_b128 v[178:181], v167 offset:50176
	ds_read_b128 v[182:185], v167 offset:51200
	ds_read_b128 v[186:189], v167 offset:52224
	ds_read_b128 v[190:193], v167 offset:53248
	ds_read_b128 v[196:199], v167 offset:54272
	ds_read_b128 v[200:203], v167 offset:55296
	ds_read_b128 v[204:207], v167 offset:56320
	global_load_lds_dwordx4 v[224:225], off
	v_lshl_add_u64 v[224:225], v[230:231], 0, s[26:27]
	s_mov_b32 m0, s49
	s_nop 0
	global_load_lds_dwordx4 v[224:225], off
	s_barrier
	s_waitcnt lgkmcnt(0)
	s_waitcnt lgkmcnt(0)
	v_mfma_f32_16x16x32_bf16 v[28:31], v[132:135], v[174:177], v[28:31]
	v_mfma_f32_16x16x32_bf16 v[24:27], v[160:163], v[174:177], v[24:27]
	v_mfma_f32_16x16x32_bf16 v[20:23], v[132:135], v[182:185], v[20:23]
	v_mfma_f32_16x16x32_bf16 v[16:19], v[160:163], v[182:185], v[16:19]
	v_mfma_f32_16x16x32_bf16 v[12:15], v[132:135], v[190:193], v[12:15]
	v_mfma_f32_16x16x32_bf16 v[8:11], v[160:163], v[190:193], v[8:11]
	v_mfma_f32_16x16x32_bf16 v[4:7], v[132:135], v[200:203], v[4:7]
	v_mfma_f32_16x16x32_bf16 v[0:3], v[160:163], v[200:203], v[0:3]
	v_mfma_f32_16x16x32_bf16 v[28:31], v[156:159], v[178:181], v[28:31]
	v_mfma_f32_16x16x32_bf16 v[24:27], v[170:173], v[178:181], v[24:27]
	v_mfma_f32_16x16x32_bf16 v[20:23], v[156:159], v[186:189], v[20:23]
	v_mfma_f32_16x16x32_bf16 v[16:19], v[170:173], v[186:189], v[16:19]
	v_mfma_f32_16x16x32_bf16 v[12:15], v[156:159], v[196:199], v[12:15]
	v_mfma_f32_16x16x32_bf16 v[8:11], v[170:173], v[196:199], v[8:11]
	v_mfma_f32_16x16x32_bf16 v[4:7], v[156:159], v[204:207], v[4:7]
	v_mfma_f32_16x16x32_bf16 v[0:3], v[170:173], v[204:207], v[0:3]
	s_barrier
	s_add_u32 s10, s36, 0x40080
	s_addc_u32 s11, s37, 0
	s_add_i32 s22, s38, s43
	v_lshl_add_u64 v[132:133], s[10:11], 0, v[138:139]
	s_mov_b32 m0, s22
	s_nop 0
	global_load_lds_dwordx4 v[132:133], off
	v_lshl_add_u64 v[132:133], s[10:11], 0, v[142:143]
	s_add_i32 m0, s22, 0x2000
	s_nop 0
	global_load_lds_dwordx4 v[132:133], off
	s_waitcnt vmcnt(6)
	s_barrier
	v_mfma_f32_16x16x32_bf16 v[92:95], v[208:211], v[174:177], v[92:95]
	v_mfma_f32_16x16x32_bf16 v[88:91], v[216:219], v[174:177], v[88:91]
	v_mfma_f32_16x16x32_bf16 v[84:87], v[208:211], v[182:185], v[84:87]
	v_mfma_f32_16x16x32_bf16 v[80:83], v[216:219], v[182:185], v[80:83]
	v_mfma_f32_16x16x32_bf16 v[76:79], v[208:211], v[190:193], v[76:79]
	v_mfma_f32_16x16x32_bf16 v[72:75], v[216:219], v[190:193], v[72:75]
	v_mfma_f32_16x16x32_bf16 v[68:71], v[208:211], v[200:203], v[68:71]
	v_mfma_f32_16x16x32_bf16 v[64:67], v[216:219], v[200:203], v[64:67]
	v_mfma_f32_16x16x32_bf16 v[92:95], v[212:215], v[178:181], v[92:95]
	v_mfma_f32_16x16x32_bf16 v[88:91], v[220:223], v[178:181], v[88:91]
	v_mfma_f32_16x16x32_bf16 v[84:87], v[212:215], v[186:189], v[84:87]
	v_mfma_f32_16x16x32_bf16 v[80:83], v[220:223], v[186:189], v[80:83]
	v_mfma_f32_16x16x32_bf16 v[76:79], v[212:215], v[196:199], v[76:79]
	v_mfma_f32_16x16x32_bf16 v[72:75], v[220:223], v[196:199], v[72:75]
	v_mfma_f32_16x16x32_bf16 v[68:71], v[212:215], v[204:207], v[68:71]
	v_mfma_f32_16x16x32_bf16 v[64:67], v[220:223], v[204:207], v[64:67]
	s_add_u32 s0, s0, 0x100
	s_addc_u32 s1, s1, 0
	s_cmp_gt_u32 s41, 13
	s_mov_b32 s22, s41
	s_barrier
	s_cbranch_scc1 .LBB0_287

.LBB0_964:
	s_add_u32 s10, s42, s46
	s_addc_u32 s56, s43, s47
	s_and_b64 s[50:51], exec, s[50:51]
	s_cselect_b32 s51, s17, s56
	s_cselect_b32 s50, s19, s10
	s_cmp_lt_u32 s78, 16
	s_cselect_b64 s[56:57], -1, 0
	s_and_b64 s[80:81], s[56:57], exec
	v_add_u32_e32 v1, s68, v191
	s_cselect_b32 s10, 0, -16
	ds_read_b128 v[132:135], v1
	ds_read_b128 v[136:139], v1 offset:1024
	ds_read_b128 v[140:143], v1 offset:2048
	ds_read_b128 v[144:147], v1 offset:3072
	s_add_i32 s10, s10, s78
	s_add_i32 s10, s10, 1
	s_and_b64 s[56:57], s[56:57], exec
	s_cselect_b32 s79, s41, s76
	s_cselect_b32 s80, s40, s75
	s_lshl_b64 s[56:57], s[10:11], 7
	s_add_u32 s10, s80, s56
	s_addc_u32 s57, s79, s57
	s_add_i32 s78, s78, 2
	s_add_u32 s56, s10, 0x40000
	s_addc_u32 s57, s57, 0
	v_lshl_add_u64 v[2:3], s[56:57], 0, v[148:149]
	s_add_i32 m0, s39, 0xc000
	ds_read_b128 v[198:201], v196
	ds_read_b128 v[202:205], v196 offset:1024
	ds_read_b128 v[206:209], v196 offset:2048
	ds_read_b128 v[210:213], v196 offset:3072
	ds_read_b128 v[214:217], v196 offset:4096
	ds_read_b128 v[218:221], v196 offset:5120
	ds_read_b128 v[222:225], v196 offset:6144
	ds_read_b128 v[226:229], v196 offset:7168
	global_load_lds_dwordx4 v[2:3], off
	v_lshl_add_u64 v[2:3], s[56:57], 0, v[152:153]
	s_add_i32 m0, s39, 0xe000
	s_nop 0
	global_load_lds_dwordx4 v[2:3], off
	s_waitcnt lgkmcnt(8)
	s_barrier
	s_waitcnt lgkmcnt(0)
	s_waitcnt lgkmcnt(0)
	v_mfma_f32_16x16x32_bf16 v[128:131], v[132:135], v[198:201], v[128:131]
	v_mfma_f32_16x16x32_bf16 v[124:127], v[140:143], v[198:201], v[124:127]
	v_mfma_f32_16x16x32_bf16 v[112:115], v[132:135], v[206:209], v[112:115]
	v_mfma_f32_16x16x32_bf16 v[108:111], v[140:143], v[206:209], v[108:111]
	v_mfma_f32_16x16x32_bf16 v[96:99], v[132:135], v[214:217], v[96:99]
	v_mfma_f32_16x16x32_bf16 v[92:95], v[140:143], v[214:217], v[92:95]
	v_mfma_f32_16x16x32_bf16 v[80:83], v[132:135], v[222:225], v[80:83]
	v_mfma_f32_16x16x32_bf16 v[76:79], v[140:143], v[222:225], v[76:79]
	v_mfma_f32_16x16x32_bf16 v[128:131], v[136:139], v[202:205], v[128:131]
	v_mfma_f32_16x16x32_bf16 v[124:127], v[144:147], v[202:205], v[124:127]
	v_mfma_f32_16x16x32_bf16 v[112:115], v[136:139], v[210:213], v[112:115]
	v_mfma_f32_16x16x32_bf16 v[108:111], v[144:147], v[210:213], v[108:111]
	v_mfma_f32_16x16x32_bf16 v[96:99], v[136:139], v[218:221], v[96:99]
	v_mfma_f32_16x16x32_bf16 v[92:95], v[144:147], v[218:221], v[92:95]
	v_mfma_f32_16x16x32_bf16 v[80:83], v[136:139], v[226:229], v[80:83]
	v_mfma_f32_16x16x32_bf16 v[76:79], v[144:147], v[226:229], v[76:79]
	s_barrier
	s_add_i32 s10, s68, s60
	v_add_u32_e32 v1, s69, v191
	v_lshl_add_u64 v[246:247], s[50:51], 0, v[150:151]
	s_mov_b32 m0, s10
	ds_read_b128 v[230:233], v1
	ds_read_b128 v[234:237], v1 offset:1024
	ds_read_b128 v[238:241], v1 offset:2048
	ds_read_b128 v[242:245], v1 offset:3072
	global_load_lds_dwordx4 v[246:247], off
	v_lshl_add_u64 v[248:249], s[50:51], 0, v[154:155]
	s_add_i32 m0, s10, 0x2000
	s_nop 0
	global_load_lds_dwordx4 v[248:249], off
	s_barrier
	s_waitcnt lgkmcnt(0)
	s_waitcnt lgkmcnt(0)
	v_mfma_f32_16x16x32_bf16 v[120:123], v[230:233], v[198:201], v[120:123]
	v_mfma_f32_16x16x32_bf16 v[116:119], v[238:241], v[198:201], v[116:119]
	v_mfma_f32_16x16x32_bf16 v[104:107], v[230:233], v[206:209], v[104:107]
	v_mfma_f32_16x16x32_bf16 v[100:103], v[238:241], v[206:209], v[100:103]
	v_mfma_f32_16x16x32_bf16 v[88:91], v[230:233], v[214:217], v[88:91]
	v_mfma_f32_16x16x32_bf16 v[84:87], v[238:241], v[214:217], v[84:87]
	v_mfma_f32_16x16x32_bf16 v[72:75], v[230:233], v[222:225], v[72:75]
	v_mfma_f32_16x16x32_bf16 v[68:71], v[238:241], v[222:225], v[68:71]
	v_mfma_f32_16x16x32_bf16 v[120:123], v[234:237], v[202:205], v[120:123]
	v_mfma_f32_16x16x32_bf16 v[116:119], v[242:245], v[202:205], v[116:119]
	v_mfma_f32_16x16x32_bf16 v[104:107], v[234:237], v[210:213], v[104:107]
	v_mfma_f32_16x16x32_bf16 v[100:103], v[242:245], v[210:213], v[100:103]
	v_mfma_f32_16x16x32_bf16 v[88:91], v[234:237], v[218:221], v[88:91]
	v_mfma_f32_16x16x32_bf16 v[84:87], v[242:245], v[218:221], v[84:87]
	v_mfma_f32_16x16x32_bf16 v[72:75], v[234:237], v[226:229], v[72:75]
	v_mfma_f32_16x16x32_bf16 v[68:71], v[242:245], v[226:229], v[68:71]
	s_mov_b32 m0, s39
	v_lshl_add_u64 v[250:251], s[48:49], 0, v[148:149]
	s_barrier
	ds_read_b128 v[198:201], v196 offset:16384
	ds_read_b128 v[202:205], v196 offset:17408
	ds_read_b128 v[206:209], v196 offset:18432
	ds_read_b128 v[210:213], v196 offset:19456
	ds_read_b128 v[214:217], v196 offset:20480
	ds_read_b128 v[218:221], v196 offset:21504
	ds_read_b128 v[222:225], v196 offset:22528
	ds_read_b128 v[226:229], v196 offset:23552
	global_load_lds_dwordx4 v[250:251], off
	v_lshl_add_u64 v[252:253], s[48:49], 0, v[152:153]
	s_mov_b32 m0, s61
	s_nop 0
	global_load_lds_dwordx4 v[252:253], off
	s_barrier
	s_waitcnt lgkmcnt(0)
	s_waitcnt lgkmcnt(0)
	v_mfma_f32_16x16x32_bf16 v[64:67], v[132:135], v[198:201], v[64:67]
	v_mfma_f32_16x16x32_bf16 v[60:63], v[140:143], v[198:201], v[60:63]
	v_mfma_f32_16x16x32_bf16 v[48:51], v[132:135], v[206:209], v[48:51]
	v_mfma_f32_16x16x32_bf16 v[44:47], v[140:143], v[206:209], v[44:47]
	v_mfma_f32_16x16x32_bf16 v[32:35], v[132:135], v[214:217], v[32:35]
	v_mfma_f32_16x16x32_bf16 v[28:31], v[140:143], v[214:217], v[28:31]
	v_mfma_f32_16x16x32_bf16 v[16:19], v[132:135], v[222:225], v[16:19]
	v_mfma_f32_16x16x32_bf16 v[12:15], v[140:143], v[222:225], v[12:15]
	v_mfma_f32_16x16x32_bf16 v[64:67], v[136:139], v[202:205], v[64:67]
	v_mfma_f32_16x16x32_bf16 v[60:63], v[144:147], v[202:205], v[60:63]
	v_mfma_f32_16x16x32_bf16 v[48:51], v[136:139], v[210:213], v[48:51]
	v_mfma_f32_16x16x32_bf16 v[44:47], v[144:147], v[210:213], v[44:47]
	v_mfma_f32_16x16x32_bf16 v[32:35], v[136:139], v[218:221], v[32:35]
	v_mfma_f32_16x16x32_bf16 v[28:31], v[144:147], v[218:221], v[28:31]
	v_mfma_f32_16x16x32_bf16 v[16:19], v[136:139], v[226:229], v[16:19]
	v_mfma_f32_16x16x32_bf16 v[12:15], v[144:147], v[226:229], v[12:15]
	s_barrier
	s_add_u32 s56, s50, 0x80000
	s_addc_u32 s57, s51, 0
	s_add_i32 s10, s69, s60
	v_lshl_add_u64 v[2:3], s[56:57], 0, v[150:151]
	s_mov_b32 m0, s10
	s_nop 0
	global_load_lds_dwordx4 v[2:3], off
	v_lshl_add_u64 v[2:3], s[56:57], 0, v[154:155]
	s_add_i32 m0, s10, 0x2000
	s_nop 0
	global_load_lds_dwordx4 v[2:3], off
	s_waitcnt vmcnt(6)
	s_barrier
	v_mfma_f32_16x16x32_bf16 v[56:59], v[230:233], v[198:201], v[56:59]
	v_mfma_f32_16x16x32_bf16 v[52:55], v[238:241], v[198:201], v[52:55]
	v_mfma_f32_16x16x32_bf16 v[40:43], v[230:233], v[206:209], v[40:43]
	v_mfma_f32_16x16x32_bf16 v[36:39], v[238:241], v[206:209], v[36:39]
	v_mfma_f32_16x16x32_bf16 v[24:27], v[230:233], v[214:217], v[24:27]
	v_mfma_f32_16x16x32_bf16 v[20:23], v[238:241], v[214:217], v[20:23]
	v_mfma_f32_16x16x32_bf16 v[8:11], v[230:233], v[222:225], v[8:11]
	v_mfma_f32_16x16x32_bf16 v[2:5], v[238:241], v[222:225], v[4:7]
	v_mfma_f32_16x16x32_bf16 v[56:59], v[234:237], v[202:205], v[56:59]
	v_mfma_f32_16x16x32_bf16 v[52:55], v[242:245], v[202:205], v[52:55]
	v_mfma_f32_16x16x32_bf16 v[40:43], v[234:237], v[210:213], v[40:43]
	v_mfma_f32_16x16x32_bf16 v[36:39], v[242:245], v[210:213], v[36:39]
	v_mfma_f32_16x16x32_bf16 v[24:27], v[234:237], v[218:221], v[24:27]
	v_mfma_f32_16x16x32_bf16 v[20:23], v[242:245], v[218:221], v[20:23]
	v_mfma_f32_16x16x32_bf16 v[8:11], v[234:237], v[226:229], v[8:11]
	v_mfma_f32_16x16x32_bf16 v[2:5], v[242:245], v[226:229], v[2:5]
	s_add_i32 s10, 0, 0x18000
	v_add_u32_e32 v1, s10, v191
	s_barrier
	ds_read_b128 v[132:135], v1
	ds_read_b128 v[136:139], v1 offset:1024
	ds_read_b128 v[140:143], v1 offset:2048
	ds_read_b128 v[144:147], v1 offset:3072
	s_add_u32 s48, s48, 0x40000
	s_addc_u32 s49, s49, 0
	s_mov_b32 m0, s62
	v_lshl_add_u64 v[6:7], s[48:49], 0, v[148:149]
	ds_read_b128 v[198:201], v196 offset:32768
	ds_read_b128 v[202:205], v196 offset:33792
	ds_read_b128 v[206:209], v196 offset:34816
	ds_read_b128 v[210:213], v196 offset:35840
	ds_read_b128 v[214:217], v196 offset:36864
	ds_read_b128 v[218:221], v196 offset:37888
	ds_read_b128 v[222:225], v196 offset:38912
	ds_read_b128 v[226:229], v196 offset:39936
	global_load_lds_dwordx4 v[6:7], off
	v_lshl_add_u64 v[6:7], s[48:49], 0, v[152:153]
	s_mov_b32 m0, s63
	s_nop 0
	global_load_lds_dwordx4 v[6:7], off
	s_waitcnt lgkmcnt(8)
	s_barrier
	s_waitcnt lgkmcnt(0)
	s_waitcnt lgkmcnt(0)
	v_mfma_f32_16x16x32_bf16 v[128:131], v[132:135], v[198:201], v[128:131]
	v_mfma_f32_16x16x32_bf16 v[124:127], v[140:143], v[198:201], v[124:127]
	v_mfma_f32_16x16x32_bf16 v[112:115], v[132:135], v[206:209], v[112:115]
	v_mfma_f32_16x16x32_bf16 v[108:111], v[140:143], v[206:209], v[108:111]
	v_mfma_f32_16x16x32_bf16 v[96:99], v[132:135], v[214:217], v[96:99]
	v_mfma_f32_16x16x32_bf16 v[92:95], v[140:143], v[214:217], v[92:95]
	v_mfma_f32_16x16x32_bf16 v[80:83], v[132:135], v[222:225], v[80:83]
	v_mfma_f32_16x16x32_bf16 v[76:79], v[140:143], v[222:225], v[76:79]
	v_mfma_f32_16x16x32_bf16 v[128:131], v[136:139], v[202:205], v[128:131]
	v_mfma_f32_16x16x32_bf16 v[124:127], v[144:147], v[202:205], v[124:127]
	v_mfma_f32_16x16x32_bf16 v[112:115], v[136:139], v[210:213], v[112:115]
	v_mfma_f32_16x16x32_bf16 v[108:111], v[144:147], v[210:213], v[108:111]
	v_mfma_f32_16x16x32_bf16 v[96:99], v[136:139], v[218:221], v[96:99]
	v_mfma_f32_16x16x32_bf16 v[92:95], v[144:147], v[218:221], v[92:95]
	v_mfma_f32_16x16x32_bf16 v[80:83], v[136:139], v[226:229], v[80:83]
	v_mfma_f32_16x16x32_bf16 v[76:79], v[144:147], v[226:229], v[76:79]
	s_barrier
	s_add_i32 s56, 0, 0x1c000
	s_add_i32 s10, s10, s60
	v_add_u32_e32 v1, s56, v191
	v_lshl_add_u64 v[6:7], v[246:247], 0, s[14:15]
	s_mov_b32 m0, s10
	ds_read_b128 v[230:233], v1
	ds_read_b128 v[234:237], v1 offset:1024
	ds_read_b128 v[238:241], v1 offset:2048
	ds_read_b128 v[242:245], v1 offset:3072
	global_load_lds_dwordx4 v[6:7], off
	v_lshl_add_u64 v[6:7], v[248:249], 0, s[14:15]
	s_add_i32 m0, s10, 0x2000
	s_nop 0
	global_load_lds_dwordx4 v[6:7], off
	s_barrier
	s_waitcnt lgkmcnt(0)
	s_waitcnt lgkmcnt(0)
	v_mfma_f32_16x16x32_bf16 v[120:123], v[230:233], v[198:201], v[120:123]
	v_mfma_f32_16x16x32_bf16 v[116:119], v[238:241], v[198:201], v[116:119]
	v_mfma_f32_16x16x32_bf16 v[104:107], v[230:233], v[206:209], v[104:107]
	v_mfma_f32_16x16x32_bf16 v[100:103], v[238:241], v[206:209], v[100:103]
	v_mfma_f32_16x16x32_bf16 v[88:91], v[230:233], v[214:217], v[88:91]
	v_mfma_f32_16x16x32_bf16 v[84:87], v[238:241], v[214:217], v[84:87]
	v_mfma_f32_16x16x32_bf16 v[72:75], v[230:233], v[222:225], v[72:75]
	v_mfma_f32_16x16x32_bf16 v[68:71], v[238:241], v[222:225], v[68:71]
	v_mfma_f32_16x16x32_bf16 v[120:123], v[234:237], v[202:205], v[120:123]
	v_mfma_f32_16x16x32_bf16 v[116:119], v[242:245], v[202:205], v[116:119]
	v_mfma_f32_16x16x32_bf16 v[104:107], v[234:237], v[210:213], v[104:107]
	v_mfma_f32_16x16x32_bf16 v[100:103], v[242:245], v[210:213], v[100:103]
	v_mfma_f32_16x16x32_bf16 v[88:91], v[234:237], v[218:221], v[88:91]
	v_mfma_f32_16x16x32_bf16 v[84:87], v[242:245], v[218:221], v[84:87]
	v_mfma_f32_16x16x32_bf16 v[72:75], v[234:237], v[226:229], v[72:75]
	v_mfma_f32_16x16x32_bf16 v[68:71], v[242:245], v[226:229], v[68:71]
	s_mov_b32 m0, s66
	v_lshl_add_u64 v[6:7], v[250:251], 0, s[14:15]
	s_barrier
	ds_read_b128 v[198:201], v196 offset:49152
	ds_read_b128 v[202:205], v196 offset:50176
	ds_read_b128 v[206:209], v196 offset:51200
	ds_read_b128 v[210:213], v196 offset:52224
	ds_read_b128 v[214:217], v196 offset:53248
	ds_read_b128 v[218:221], v196 offset:54272
	ds_read_b128 v[222:225], v196 offset:55296
	ds_read_b128 v[226:229], v196 offset:56320
	global_load_lds_dwordx4 v[6:7], off
	v_lshl_add_u64 v[6:7], v[252:253], 0, s[14:15]
	s_mov_b32 m0, s67
	s_nop 0
	global_load_lds_dwordx4 v[6:7], off
	s_barrier
	s_waitcnt lgkmcnt(0)
	s_waitcnt lgkmcnt(0)
	v_mfma_f32_16x16x32_bf16 v[64:67], v[132:135], v[198:201], v[64:67]
	v_mfma_f32_16x16x32_bf16 v[60:63], v[140:143], v[198:201], v[60:63]
	v_mfma_f32_16x16x32_bf16 v[48:51], v[132:135], v[206:209], v[48:51]
	v_mfma_f32_16x16x32_bf16 v[44:47], v[140:143], v[206:209], v[44:47]
	v_mfma_f32_16x16x32_bf16 v[32:35], v[132:135], v[214:217], v[32:35]
	v_mfma_f32_16x16x32_bf16 v[28:31], v[140:143], v[214:217], v[28:31]
	v_mfma_f32_16x16x32_bf16 v[16:19], v[132:135], v[222:225], v[16:19]
	v_mfma_f32_16x16x32_bf16 v[12:15], v[140:143], v[222:225], v[12:15]
	v_mfma_f32_16x16x32_bf16 v[64:67], v[136:139], v[202:205], v[64:67]
	v_mfma_f32_16x16x32_bf16 v[60:63], v[144:147], v[202:205], v[60:63]
	v_mfma_f32_16x16x32_bf16 v[48:51], v[136:139], v[210:213], v[48:51]
	v_mfma_f32_16x16x32_bf16 v[44:47], v[144:147], v[210:213], v[44:47]
	v_mfma_f32_16x16x32_bf16 v[32:35], v[136:139], v[218:221], v[32:35]
	v_mfma_f32_16x16x32_bf16 v[28:31], v[144:147], v[218:221], v[28:31]
	v_mfma_f32_16x16x32_bf16 v[16:19], v[136:139], v[226:229], v[16:19]
	v_mfma_f32_16x16x32_bf16 v[12:15], v[144:147], v[226:229], v[12:15]
	s_barrier
	s_add_u32 s48, s50, 0x80080
	s_addc_u32 s49, s51, 0
	s_add_i32 s10, s56, s60
	v_lshl_add_u64 v[6:7], s[48:49], 0, v[150:151]
	s_mov_b32 m0, s10
	s_nop 0
	global_load_lds_dwordx4 v[6:7], off
	v_lshl_add_u64 v[6:7], s[48:49], 0, v[154:155]
	s_add_i32 m0, s10, 0x2000
	s_nop 0
	global_load_lds_dwordx4 v[6:7], off
	s_waitcnt vmcnt(6)
	s_barrier
	v_mfma_f32_16x16x32_bf16 v[56:59], v[230:233], v[198:201], v[56:59]
	v_mfma_f32_16x16x32_bf16 v[52:55], v[238:241], v[198:201], v[52:55]
	v_mfma_f32_16x16x32_bf16 v[40:43], v[230:233], v[206:209], v[40:43]
	v_mfma_f32_16x16x32_bf16 v[36:39], v[238:241], v[206:209], v[36:39]
	v_mfma_f32_16x16x32_bf16 v[24:27], v[230:233], v[214:217], v[24:27]
	v_mfma_f32_16x16x32_bf16 v[20:23], v[238:241], v[214:217], v[20:23]
	v_mfma_f32_16x16x32_bf16 v[6:9], v[230:233], v[222:225], v[8:11]
	v_mfma_f32_16x16x32_bf16 v[2:5], v[238:241], v[222:225], v[2:5]
	v_mfma_f32_16x16x32_bf16 v[56:59], v[234:237], v[202:205], v[56:59]
	v_mfma_f32_16x16x32_bf16 v[52:55], v[242:245], v[202:205], v[52:55]
	v_mfma_f32_16x16x32_bf16 v[40:43], v[234:237], v[210:213], v[40:43]
	v_mfma_f32_16x16x32_bf16 v[36:39], v[242:245], v[210:213], v[36:39]
	v_mfma_f32_16x16x32_bf16 v[24:27], v[234:237], v[218:221], v[24:27]
	v_mfma_f32_16x16x32_bf16 v[20:23], v[242:245], v[218:221], v[20:23]
	v_mfma_f32_16x16x32_bf16 v[8:11], v[234:237], v[226:229], v[6:9]
	v_mfma_f32_16x16x32_bf16 v[4:7], v[242:245], v[226:229], v[2:5]
	s_add_u32 s46, s46, 0x100
	s_addc_u32 s47, s47, 0
	s_cmp_ge_i32 s78, s74
	s_barrier
	s_cbranch_scc1 .LBB0_972

.LBB0_1184:
	v_add_u32_e32 v164, s62, v149
	ds_read_b128 v[152:155], v164
	ds_read_b128 v[156:159], v164 offset:1024
	ds_read_b128 v[160:163], v164 offset:2048
	ds_read_b128 v[164:167], v164 offset:3072
	s_add_u32 s10, s72, s4
	s_addc_u32 s46, s73, s5
	s_and_b64 s[44:45], exec, s[44:45]
	s_cselect_b32 s45, s23, s46
	s_cselect_b32 s44, s71, s10
	v_lshl_add_u64 v[192:193], v[144:145], 0, s[4:5]
	s_add_i32 m0, s39, 0xc000
	ds_read_b128 v[168:171], v151
	ds_read_b128 v[172:175], v151 offset:1024
	ds_read_b128 v[176:179], v151 offset:2048
	ds_read_b128 v[180:183], v151 offset:3072
	ds_read_b128 v[184:187], v151 offset:4096
	ds_read_b128 v[188:191], v151 offset:5120
	ds_read_b128 v[196:199], v151 offset:6144
	ds_read_b128 v[200:203], v151 offset:7168
	global_load_lds_dwordx4 v[192:193], off
	v_lshl_add_u64 v[192:193], v[146:147], 0, s[4:5]
	s_add_i32 m0, s39, 0xe000
	s_nop 0
	global_load_lds_dwordx4 v[192:193], off
	s_waitcnt lgkmcnt(8)
	s_barrier
	s_waitcnt lgkmcnt(0)
	s_waitcnt lgkmcnt(0)
	v_mfma_f32_16x16x32_bf16 v[124:127], v[152:155], v[168:171], v[124:127]
	v_mfma_f32_16x16x32_bf16 v[120:123], v[160:163], v[168:171], v[120:123]
	v_mfma_f32_16x16x32_bf16 v[108:111], v[152:155], v[176:179], v[108:111]
	v_mfma_f32_16x16x32_bf16 v[104:107], v[160:163], v[176:179], v[104:107]
	v_mfma_f32_16x16x32_bf16 v[92:95], v[152:155], v[184:187], v[92:95]
	v_mfma_f32_16x16x32_bf16 v[88:91], v[160:163], v[184:187], v[88:91]
	v_mfma_f32_16x16x32_bf16 v[76:79], v[152:155], v[196:199], v[76:79]
	v_mfma_f32_16x16x32_bf16 v[72:75], v[160:163], v[196:199], v[72:75]
	v_mfma_f32_16x16x32_bf16 v[124:127], v[156:159], v[172:175], v[124:127]
	v_mfma_f32_16x16x32_bf16 v[120:123], v[164:167], v[172:175], v[120:123]
	v_mfma_f32_16x16x32_bf16 v[108:111], v[156:159], v[180:183], v[108:111]
	v_mfma_f32_16x16x32_bf16 v[104:107], v[164:167], v[180:183], v[104:107]
	v_mfma_f32_16x16x32_bf16 v[92:95], v[156:159], v[188:191], v[92:95]
	v_mfma_f32_16x16x32_bf16 v[88:91], v[164:167], v[188:191], v[88:91]
	v_mfma_f32_16x16x32_bf16 v[76:79], v[156:159], v[200:203], v[76:79]
	v_mfma_f32_16x16x32_bf16 v[72:75], v[164:167], v[200:203], v[72:75]
	s_barrier
	v_add_u32_e32 v192, s63, v149
	s_add_i32 s10, s62, s50
	ds_read_b128 v[204:207], v192
	ds_read_b128 v[208:211], v192 offset:1024
	ds_read_b128 v[212:215], v192 offset:2048
	ds_read_b128 v[216:219], v192 offset:3072
	v_lshl_add_u64 v[192:193], s[44:45], 0, v[132:133]
	s_mov_b32 m0, s10
	v_lshl_add_u64 v[220:221], s[44:45], 0, v[128:129]
	global_load_lds_dwordx4 v[192:193], off
	s_add_i32 m0, s10, 0x2000
	s_nop 0
	global_load_lds_dwordx4 v[220:221], off
	s_barrier
	s_waitcnt lgkmcnt(0)
	s_waitcnt lgkmcnt(0)
	v_mfma_f32_16x16x32_bf16 v[116:119], v[204:207], v[168:171], v[116:119]
	v_mfma_f32_16x16x32_bf16 v[112:115], v[212:215], v[168:171], v[112:115]
	v_mfma_f32_16x16x32_bf16 v[100:103], v[204:207], v[176:179], v[100:103]
	v_mfma_f32_16x16x32_bf16 v[96:99], v[212:215], v[176:179], v[96:99]
	v_mfma_f32_16x16x32_bf16 v[84:87], v[204:207], v[184:187], v[84:87]
	v_mfma_f32_16x16x32_bf16 v[80:83], v[212:215], v[184:187], v[80:83]
	v_mfma_f32_16x16x32_bf16 v[68:71], v[204:207], v[196:199], v[68:71]
	v_mfma_f32_16x16x32_bf16 v[64:67], v[212:215], v[196:199], v[64:67]
	v_mfma_f32_16x16x32_bf16 v[116:119], v[208:211], v[172:175], v[116:119]
	v_mfma_f32_16x16x32_bf16 v[112:115], v[216:219], v[172:175], v[112:115]
	v_mfma_f32_16x16x32_bf16 v[100:103], v[208:211], v[180:183], v[100:103]
	v_mfma_f32_16x16x32_bf16 v[96:99], v[216:219], v[180:183], v[96:99]
	v_mfma_f32_16x16x32_bf16 v[84:87], v[208:211], v[188:191], v[84:87]
	v_mfma_f32_16x16x32_bf16 v[80:83], v[216:219], v[188:191], v[80:83]
	v_mfma_f32_16x16x32_bf16 v[68:71], v[208:211], v[200:203], v[68:71]
	v_mfma_f32_16x16x32_bf16 v[64:67], v[216:219], v[200:203], v[64:67]
	s_mov_b32 m0, s39
	v_lshl_add_u64 v[222:223], s[42:43], 0, v[134:135]
	s_barrier
	ds_read_b128 v[168:171], v151 offset:16384
	ds_read_b128 v[172:175], v151 offset:17408
	ds_read_b128 v[176:179], v151 offset:18432
	ds_read_b128 v[180:183], v151 offset:19456
	ds_read_b128 v[184:187], v151 offset:20480
	ds_read_b128 v[188:191], v151 offset:21504
	ds_read_b128 v[196:199], v151 offset:22528
	ds_read_b128 v[200:203], v151 offset:23552
	global_load_lds_dwordx4 v[222:223], off
	v_lshl_add_u64 v[224:225], s[42:43], 0, v[130:131]
	s_mov_b32 m0, s53
	s_nop 0
	global_load_lds_dwordx4 v[224:225], off
	s_barrier
	s_waitcnt lgkmcnt(0)
	s_waitcnt lgkmcnt(0)
	v_mfma_f32_16x16x32_bf16 v[60:63], v[152:155], v[168:171], v[60:63]
	v_mfma_f32_16x16x32_bf16 v[56:59], v[160:163], v[168:171], v[56:59]
	v_mfma_f32_16x16x32_bf16 v[44:47], v[152:155], v[176:179], v[44:47]
	v_mfma_f32_16x16x32_bf16 v[40:43], v[160:163], v[176:179], v[40:43]
	v_mfma_f32_16x16x32_bf16 v[28:31], v[152:155], v[184:187], v[28:31]
	v_mfma_f32_16x16x32_bf16 v[24:27], v[160:163], v[184:187], v[24:27]
	v_mfma_f32_16x16x32_bf16 v[12:15], v[152:155], v[196:199], v[12:15]
	v_mfma_f32_16x16x32_bf16 v[8:11], v[160:163], v[196:199], v[8:11]
	v_mfma_f32_16x16x32_bf16 v[60:63], v[156:159], v[172:175], v[60:63]
	v_mfma_f32_16x16x32_bf16 v[56:59], v[164:167], v[172:175], v[56:59]
	v_mfma_f32_16x16x32_bf16 v[44:47], v[156:159], v[180:183], v[44:47]
	v_mfma_f32_16x16x32_bf16 v[40:43], v[164:167], v[180:183], v[40:43]
	v_mfma_f32_16x16x32_bf16 v[28:31], v[156:159], v[188:191], v[28:31]
	v_mfma_f32_16x16x32_bf16 v[24:27], v[164:167], v[188:191], v[24:27]
	v_mfma_f32_16x16x32_bf16 v[12:15], v[156:159], v[200:203], v[12:15]
	v_mfma_f32_16x16x32_bf16 v[8:11], v[164:167], v[200:203], v[8:11]
	s_barrier
	s_add_u32 s46, s44, 0x40000
	s_addc_u32 s47, s45, 0
	s_add_i32 s10, s63, s50
	v_lshl_add_u64 v[152:153], s[46:47], 0, v[132:133]
	s_mov_b32 m0, s10
	s_nop 0
	global_load_lds_dwordx4 v[152:153], off
	v_lshl_add_u64 v[152:153], s[46:47], 0, v[128:129]
	s_add_i32 m0, s10, 0x2000
	s_nop 0
	global_load_lds_dwordx4 v[152:153], off
	s_waitcnt vmcnt(6)
	s_barrier
	v_mfma_f32_16x16x32_bf16 v[52:55], v[204:207], v[168:171], v[52:55]
	v_mfma_f32_16x16x32_bf16 v[48:51], v[212:215], v[168:171], v[48:51]
	v_mfma_f32_16x16x32_bf16 v[36:39], v[204:207], v[176:179], v[36:39]
	v_mfma_f32_16x16x32_bf16 v[32:35], v[212:215], v[176:179], v[32:35]
	v_mfma_f32_16x16x32_bf16 v[20:23], v[204:207], v[184:187], v[20:23]
	v_mfma_f32_16x16x32_bf16 v[16:19], v[212:215], v[184:187], v[16:19]
	v_mfma_f32_16x16x32_bf16 v[4:7], v[204:207], v[196:199], v[4:7]
	v_mfma_f32_16x16x32_bf16 v[0:3], v[212:215], v[196:199], v[0:3]
	v_mfma_f32_16x16x32_bf16 v[52:55], v[208:211], v[172:175], v[52:55]
	v_mfma_f32_16x16x32_bf16 v[48:51], v[216:219], v[172:175], v[48:51]
	v_mfma_f32_16x16x32_bf16 v[36:39], v[208:211], v[180:183], v[36:39]
	v_mfma_f32_16x16x32_bf16 v[32:35], v[216:219], v[180:183], v[32:35]
	v_mfma_f32_16x16x32_bf16 v[20:23], v[208:211], v[188:191], v[20:23]
	v_mfma_f32_16x16x32_bf16 v[16:19], v[216:219], v[188:191], v[16:19]
	v_mfma_f32_16x16x32_bf16 v[4:7], v[208:211], v[200:203], v[4:7]
	v_mfma_f32_16x16x32_bf16 v[0:3], v[216:219], v[200:203], v[0:3]
	s_add_i32 s10, 0, 0x18000
	v_add_u32_e32 v164, s10, v149
	s_barrier
	ds_read_b128 v[152:155], v164
	ds_read_b128 v[156:159], v164 offset:1024
	ds_read_b128 v[160:163], v164 offset:2048
	ds_read_b128 v[164:167], v164 offset:3072
	s_add_u32 s42, s42, 0x40000
	s_addc_u32 s43, s43, 0
	s_mov_b32 m0, s54
	v_lshl_add_u64 v[204:205], s[42:43], 0, v[134:135]
	ds_read_b128 v[168:171], v151 offset:32768
	ds_read_b128 v[172:175], v151 offset:33792
	ds_read_b128 v[176:179], v151 offset:34816
	ds_read_b128 v[180:183], v151 offset:35840
	ds_read_b128 v[184:187], v151 offset:36864
	ds_read_b128 v[188:191], v151 offset:37888
	ds_read_b128 v[196:199], v151 offset:38912
	ds_read_b128 v[200:203], v151 offset:39936
	global_load_lds_dwordx4 v[204:205], off
	v_lshl_add_u64 v[204:205], s[42:43], 0, v[130:131]
	s_mov_b32 m0, s55
	s_nop 0
	global_load_lds_dwordx4 v[204:205], off
	s_waitcnt lgkmcnt(8)
	s_barrier
	s_waitcnt lgkmcnt(0)
	s_waitcnt lgkmcnt(0)
	v_mfma_f32_16x16x32_bf16 v[124:127], v[152:155], v[168:171], v[124:127]
	v_mfma_f32_16x16x32_bf16 v[120:123], v[160:163], v[168:171], v[120:123]
	v_mfma_f32_16x16x32_bf16 v[108:111], v[152:155], v[176:179], v[108:111]
	v_mfma_f32_16x16x32_bf16 v[104:107], v[160:163], v[176:179], v[104:107]
	v_mfma_f32_16x16x32_bf16 v[92:95], v[152:155], v[184:187], v[92:95]
	v_mfma_f32_16x16x32_bf16 v[88:91], v[160:163], v[184:187], v[88:91]
	v_mfma_f32_16x16x32_bf16 v[76:79], v[152:155], v[196:199], v[76:79]
	v_mfma_f32_16x16x32_bf16 v[72:75], v[160:163], v[196:199], v[72:75]
	v_mfma_f32_16x16x32_bf16 v[124:127], v[156:159], v[172:175], v[124:127]
	v_mfma_f32_16x16x32_bf16 v[120:123], v[164:167], v[172:175], v[120:123]
	v_mfma_f32_16x16x32_bf16 v[108:111], v[156:159], v[180:183], v[108:111]
	v_mfma_f32_16x16x32_bf16 v[104:107], v[164:167], v[180:183], v[104:107]
	v_mfma_f32_16x16x32_bf16 v[92:95], v[156:159], v[188:191], v[92:95]
	v_mfma_f32_16x16x32_bf16 v[88:91], v[164:167], v[188:191], v[88:91]
	v_mfma_f32_16x16x32_bf16 v[76:79], v[156:159], v[200:203], v[76:79]
	v_mfma_f32_16x16x32_bf16 v[72:75], v[164:167], v[200:203], v[72:75]
	s_barrier
	s_add_i32 s46, 0, 0x1c000
	s_add_i32 s10, s10, s50
	v_add_u32_e32 v216, s46, v149
	v_lshl_add_u64 v[192:193], v[192:193], 0, s[12:13]
	s_mov_b32 m0, s10
	ds_read_b128 v[204:207], v216
	ds_read_b128 v[208:211], v216 offset:1024
	ds_read_b128 v[212:215], v216 offset:2048
	ds_read_b128 v[216:219], v216 offset:3072
	global_load_lds_dwordx4 v[192:193], off
	v_lshl_add_u64 v[192:193], v[220:221], 0, s[12:13]
	s_add_i32 m0, s10, 0x2000
	s_nop 0
	global_load_lds_dwordx4 v[192:193], off
	s_barrier
	s_waitcnt lgkmcnt(0)
	s_waitcnt lgkmcnt(0)
	v_mfma_f32_16x16x32_bf16 v[116:119], v[204:207], v[168:171], v[116:119]
	v_mfma_f32_16x16x32_bf16 v[112:115], v[212:215], v[168:171], v[112:115]
	v_mfma_f32_16x16x32_bf16 v[100:103], v[204:207], v[176:179], v[100:103]
	v_mfma_f32_16x16x32_bf16 v[96:99], v[212:215], v[176:179], v[96:99]
	v_mfma_f32_16x16x32_bf16 v[84:87], v[204:207], v[184:187], v[84:87]
	v_mfma_f32_16x16x32_bf16 v[80:83], v[212:215], v[184:187], v[80:83]
	v_mfma_f32_16x16x32_bf16 v[68:71], v[204:207], v[196:199], v[68:71]
	v_mfma_f32_16x16x32_bf16 v[64:67], v[212:215], v[196:199], v[64:67]
	v_mfma_f32_16x16x32_bf16 v[116:119], v[208:211], v[172:175], v[116:119]
	v_mfma_f32_16x16x32_bf16 v[112:115], v[216:219], v[172:175], v[112:115]
	v_mfma_f32_16x16x32_bf16 v[100:103], v[208:211], v[180:183], v[100:103]
	v_mfma_f32_16x16x32_bf16 v[96:99], v[216:219], v[180:183], v[96:99]
	v_mfma_f32_16x16x32_bf16 v[84:87], v[208:211], v[188:191], v[84:87]
	v_mfma_f32_16x16x32_bf16 v[80:83], v[216:219], v[188:191], v[80:83]
	v_mfma_f32_16x16x32_bf16 v[68:71], v[208:211], v[200:203], v[68:71]
	v_mfma_f32_16x16x32_bf16 v[64:67], v[216:219], v[200:203], v[64:67]
	s_mov_b32 m0, s58
	v_lshl_add_u64 v[192:193], v[222:223], 0, s[12:13]
	s_barrier
	ds_read_b128 v[168:171], v151 offset:49152
	ds_read_b128 v[172:175], v151 offset:50176
	ds_read_b128 v[176:179], v151 offset:51200
	ds_read_b128 v[180:183], v151 offset:52224
	ds_read_b128 v[184:187], v151 offset:53248
	ds_read_b128 v[188:191], v151 offset:54272
	ds_read_b128 v[196:199], v151 offset:55296
	ds_read_b128 v[200:203], v151 offset:56320
	global_load_lds_dwordx4 v[192:193], off
	v_lshl_add_u64 v[192:193], v[224:225], 0, s[12:13]
	s_mov_b32 m0, s59
	s_nop 0
	global_load_lds_dwordx4 v[192:193], off
	s_barrier
	s_waitcnt lgkmcnt(0)
	s_waitcnt lgkmcnt(0)
	v_mfma_f32_16x16x32_bf16 v[60:63], v[152:155], v[168:171], v[60:63]
	v_mfma_f32_16x16x32_bf16 v[56:59], v[160:163], v[168:171], v[56:59]
	v_mfma_f32_16x16x32_bf16 v[44:47], v[152:155], v[176:179], v[44:47]
	v_mfma_f32_16x16x32_bf16 v[40:43], v[160:163], v[176:179], v[40:43]
	v_mfma_f32_16x16x32_bf16 v[28:31], v[152:155], v[184:187], v[28:31]
	v_mfma_f32_16x16x32_bf16 v[24:27], v[160:163], v[184:187], v[24:27]
	v_mfma_f32_16x16x32_bf16 v[12:15], v[152:155], v[196:199], v[12:15]
	v_mfma_f32_16x16x32_bf16 v[8:11], v[160:163], v[196:199], v[8:11]
	v_mfma_f32_16x16x32_bf16 v[60:63], v[156:159], v[172:175], v[60:63]
	v_mfma_f32_16x16x32_bf16 v[56:59], v[164:167], v[172:175], v[56:59]
	v_mfma_f32_16x16x32_bf16 v[44:47], v[156:159], v[180:183], v[44:47]
	v_mfma_f32_16x16x32_bf16 v[40:43], v[164:167], v[180:183], v[40:43]
	v_mfma_f32_16x16x32_bf16 v[28:31], v[156:159], v[188:191], v[28:31]
	v_mfma_f32_16x16x32_bf16 v[24:27], v[164:167], v[188:191], v[24:27]
	v_mfma_f32_16x16x32_bf16 v[12:15], v[156:159], v[200:203], v[12:15]
	v_mfma_f32_16x16x32_bf16 v[8:11], v[164:167], v[200:203], v[8:11]
	s_barrier
	s_add_u32 s42, s44, 0x40080
	s_addc_u32 s43, s45, 0
	s_add_i32 s10, s46, s50
	v_lshl_add_u64 v[152:153], s[42:43], 0, v[132:133]
	s_mov_b32 m0, s10
	s_nop 0
	global_load_lds_dwordx4 v[152:153], off
	v_lshl_add_u64 v[152:153], s[42:43], 0, v[128:129]
	s_add_i32 m0, s10, 0x2000
	s_nop 0
	global_load_lds_dwordx4 v[152:153], off
	s_waitcnt vmcnt(6)
	s_barrier
	v_mfma_f32_16x16x32_bf16 v[52:55], v[204:207], v[168:171], v[52:55]
	v_mfma_f32_16x16x32_bf16 v[48:51], v[212:215], v[168:171], v[48:51]
	v_mfma_f32_16x16x32_bf16 v[36:39], v[204:207], v[176:179], v[36:39]
	v_mfma_f32_16x16x32_bf16 v[32:35], v[212:215], v[176:179], v[32:35]
	v_mfma_f32_16x16x32_bf16 v[20:23], v[204:207], v[184:187], v[20:23]
	v_mfma_f32_16x16x32_bf16 v[16:19], v[212:215], v[184:187], v[16:19]
	v_mfma_f32_16x16x32_bf16 v[4:7], v[204:207], v[196:199], v[4:7]
	v_mfma_f32_16x16x32_bf16 v[0:3], v[212:215], v[196:199], v[0:3]
	v_mfma_f32_16x16x32_bf16 v[52:55], v[208:211], v[172:175], v[52:55]
	v_mfma_f32_16x16x32_bf16 v[48:51], v[216:219], v[172:175], v[48:51]
	v_mfma_f32_16x16x32_bf16 v[36:39], v[208:211], v[180:183], v[36:39]
	v_mfma_f32_16x16x32_bf16 v[32:35], v[216:219], v[180:183], v[32:35]
	v_mfma_f32_16x16x32_bf16 v[20:23], v[208:211], v[188:191], v[20:23]
	v_mfma_f32_16x16x32_bf16 v[16:19], v[216:219], v[188:191], v[16:19]
	v_mfma_f32_16x16x32_bf16 v[4:7], v[208:211], v[200:203], v[4:7]
	v_mfma_f32_16x16x32_bf16 v[0:3], v[216:219], v[200:203], v[0:3]
	s_add_u32 s4, s4, 0x100
	s_addc_u32 s5, s5, 0
	s_cmp_gt_u32 s74, 13
	s_mov_b32 s10, s74
	s_barrier
	s_cbranch_scc1 .LBB0_1177

.LBB0_1260:
	s_cmp_lt_u32 s79, 0x100000
	s_cselect_b64 s[54:55], -1, 0
	s_and_b64 s[80:81], s[54:55], exec
	s_cselect_b32 s0, 0, 0xfff00000
	s_add_i32 s0, s0, s79
	s_add_i32 s0, s0, 1
	v_add_u32_e32 v140, s66, v155
	s_and_b64 s[54:55], s[54:55], exec
	ds_read_b128 v[128:131], v140
	ds_read_b128 v[132:135], v140 offset:1024
	ds_read_b128 v[136:139], v140 offset:2048
	ds_read_b128 v[140:143], v140 offset:3072
	s_cselect_b32 s80, s43, s77
	s_cselect_b32 s81, s42, s39
	s_lshl_b64 s[54:55], s[0:1], 7
	s_add_u32 s0, s81, s54
	s_addc_u32 s55, s80, s55
	s_add_i32 s79, s79, 2
	s_add_u32 s54, s44, s48
	s_addc_u32 s80, s45, s49
	s_and_b64 s[52:53], exec, s[52:53]
	s_cselect_b32 s53, s19, s80
	s_cselect_b32 s52, s21, s54
	s_add_u32 s54, s0, 0x100000
	s_addc_u32 s55, s55, 0
	v_lshl_add_u64 v[152:153], s[54:55], 0, v[144:145]
	s_add_i32 m0, s41, 0xc000
	ds_read_b128 v[158:161], v157
	ds_read_b128 v[162:165], v157 offset:1024
	ds_read_b128 v[166:169], v157 offset:2048
	ds_read_b128 v[170:173], v157 offset:3072
	ds_read_b128 v[174:177], v157 offset:4096
	ds_read_b128 v[178:181], v157 offset:5120
	ds_read_b128 v[182:185], v157 offset:6144
	ds_read_b128 v[186:189], v157 offset:7168
	global_load_lds_dwordx4 v[152:153], off
	v_lshl_add_u64 v[152:153], s[54:55], 0, v[148:149]
	s_add_i32 m0, s41, 0xe000
	s_nop 0
	global_load_lds_dwordx4 v[152:153], off
	s_waitcnt lgkmcnt(8)
	s_barrier
	s_waitcnt lgkmcnt(0)
	s_waitcnt lgkmcnt(0)
	v_mfma_f32_16x16x32_bf16 v[124:127], v[128:131], v[158:161], v[124:127]
	v_mfma_f32_16x16x32_bf16 v[120:123], v[136:139], v[158:161], v[120:123]
	v_mfma_f32_16x16x32_bf16 v[116:119], v[128:131], v[166:169], v[116:119]
	v_mfma_f32_16x16x32_bf16 v[112:115], v[136:139], v[166:169], v[112:115]
	v_mfma_f32_16x16x32_bf16 v[108:111], v[128:131], v[174:177], v[108:111]
	v_mfma_f32_16x16x32_bf16 v[100:103], v[136:139], v[174:177], v[100:103]
	v_mfma_f32_16x16x32_bf16 v[76:79], v[128:131], v[182:185], v[76:79]
	v_mfma_f32_16x16x32_bf16 v[72:75], v[136:139], v[182:185], v[72:75]
	v_mfma_f32_16x16x32_bf16 v[124:127], v[132:135], v[162:165], v[124:127]
	v_mfma_f32_16x16x32_bf16 v[120:123], v[140:143], v[162:165], v[120:123]
	v_mfma_f32_16x16x32_bf16 v[116:119], v[132:135], v[170:173], v[116:119]
	v_mfma_f32_16x16x32_bf16 v[112:115], v[140:143], v[170:173], v[112:115]
	v_mfma_f32_16x16x32_bf16 v[108:111], v[132:135], v[178:181], v[108:111]
	v_mfma_f32_16x16x32_bf16 v[100:103], v[140:143], v[178:181], v[100:103]
	v_mfma_f32_16x16x32_bf16 v[76:79], v[132:135], v[186:189], v[76:79]
	v_mfma_f32_16x16x32_bf16 v[72:75], v[140:143], v[186:189], v[72:75]
	s_barrier
	v_add_u32_e32 v152, s67, v155
	s_add_i32 s0, s66, s58
	ds_read_b128 v[190:193], v152
	ds_read_b128 v[196:199], v152 offset:1024
	ds_read_b128 v[200:203], v152 offset:2048
	ds_read_b128 v[204:207], v152 offset:3072
	v_lshl_add_u64 v[152:153], s[52:53], 0, v[146:147]
	s_mov_b32 m0, s0
	v_lshl_add_u64 v[208:209], s[52:53], 0, v[150:151]
	global_load_lds_dwordx4 v[152:153], off
	s_add_i32 m0, s0, 0x2000
	s_nop 0
	global_load_lds_dwordx4 v[208:209], off
	s_barrier
	s_waitcnt lgkmcnt(0)
	s_waitcnt lgkmcnt(0)
	v_mfma_f32_16x16x32_bf16 v[104:107], v[190:193], v[158:161], v[104:107]
	v_mfma_f32_16x16x32_bf16 v[96:99], v[200:203], v[158:161], v[96:99]
	v_mfma_f32_16x16x32_bf16 v[92:95], v[190:193], v[166:169], v[92:95]
	v_mfma_f32_16x16x32_bf16 v[88:91], v[200:203], v[166:169], v[88:91]
	v_mfma_f32_16x16x32_bf16 v[84:87], v[190:193], v[174:177], v[84:87]
	v_mfma_f32_16x16x32_bf16 v[80:83], v[200:203], v[174:177], v[80:83]
	v_mfma_f32_16x16x32_bf16 v[68:71], v[190:193], v[182:185], v[68:71]
	v_mfma_f32_16x16x32_bf16 v[64:67], v[200:203], v[182:185], v[64:67]
	v_mfma_f32_16x16x32_bf16 v[104:107], v[196:199], v[162:165], v[104:107]
	v_mfma_f32_16x16x32_bf16 v[96:99], v[204:207], v[162:165], v[96:99]
	v_mfma_f32_16x16x32_bf16 v[92:95], v[196:199], v[170:173], v[92:95]
	v_mfma_f32_16x16x32_bf16 v[88:91], v[204:207], v[170:173], v[88:91]
	v_mfma_f32_16x16x32_bf16 v[84:87], v[196:199], v[178:181], v[84:87]
	v_mfma_f32_16x16x32_bf16 v[80:83], v[204:207], v[178:181], v[80:83]
	v_mfma_f32_16x16x32_bf16 v[68:71], v[196:199], v[186:189], v[68:71]
	v_mfma_f32_16x16x32_bf16 v[64:67], v[204:207], v[186:189], v[64:67]
	s_mov_b32 m0, s41
	v_lshl_add_u64 v[210:211], s[50:51], 0, v[144:145]
	s_barrier
	ds_read_b128 v[158:161], v157 offset:16384
	ds_read_b128 v[162:165], v157 offset:17408
	ds_read_b128 v[166:169], v157 offset:18432
	ds_read_b128 v[170:173], v157 offset:19456
	ds_read_b128 v[174:177], v157 offset:20480
	ds_read_b128 v[178:181], v157 offset:21504
	ds_read_b128 v[182:185], v157 offset:22528
	ds_read_b128 v[186:189], v157 offset:23552
	global_load_lds_dwordx4 v[210:211], off
	v_lshl_add_u64 v[212:213], s[50:51], 0, v[148:149]
	s_mov_b32 m0, s59
	s_nop 0
	global_load_lds_dwordx4 v[212:213], off
	s_barrier
	s_waitcnt lgkmcnt(0)
	s_waitcnt lgkmcnt(0)
	v_mfma_f32_16x16x32_bf16 v[60:63], v[128:131], v[158:161], v[60:63]
	v_mfma_f32_16x16x32_bf16 v[56:59], v[136:139], v[158:161], v[56:59]
	v_mfma_f32_16x16x32_bf16 v[48:51], v[128:131], v[166:169], v[48:51]
	v_mfma_f32_16x16x32_bf16 v[40:43], v[136:139], v[166:169], v[40:43]
	v_mfma_f32_16x16x32_bf16 v[32:35], v[128:131], v[174:177], v[32:35]
	v_mfma_f32_16x16x32_bf16 v[24:27], v[136:139], v[174:177], v[24:27]
	v_mfma_f32_16x16x32_bf16 v[16:19], v[128:131], v[182:185], v[16:19]
	v_mfma_f32_16x16x32_bf16 v[8:11], v[136:139], v[182:185], v[8:11]
	v_mfma_f32_16x16x32_bf16 v[60:63], v[132:135], v[162:165], v[60:63]
	v_mfma_f32_16x16x32_bf16 v[56:59], v[140:143], v[162:165], v[56:59]
	v_mfma_f32_16x16x32_bf16 v[48:51], v[132:135], v[170:173], v[48:51]
	v_mfma_f32_16x16x32_bf16 v[40:43], v[140:143], v[170:173], v[40:43]
	v_mfma_f32_16x16x32_bf16 v[32:35], v[132:135], v[178:181], v[32:35]
	v_mfma_f32_16x16x32_bf16 v[24:27], v[140:143], v[178:181], v[24:27]
	v_mfma_f32_16x16x32_bf16 v[16:19], v[132:135], v[186:189], v[16:19]
	v_mfma_f32_16x16x32_bf16 v[8:11], v[140:143], v[186:189], v[8:11]
	s_barrier
	s_add_u32 s54, s52, 0x100000
	s_addc_u32 s55, s53, 0
	s_add_i32 s0, s67, s58
	v_lshl_add_u64 v[128:129], s[54:55], 0, v[146:147]
	s_mov_b32 m0, s0
	s_nop 0
	global_load_lds_dwordx4 v[128:129], off
	v_lshl_add_u64 v[128:129], s[54:55], 0, v[150:151]
	s_add_i32 m0, s0, 0x2000
	s_nop 0
	global_load_lds_dwordx4 v[128:129], off
	s_waitcnt vmcnt(6)
	s_barrier
	v_mfma_f32_16x16x32_bf16 v[52:55], v[190:193], v[158:161], v[52:55]
	v_mfma_f32_16x16x32_bf16 v[44:47], v[200:203], v[158:161], v[44:47]
	v_mfma_f32_16x16x32_bf16 v[36:39], v[190:193], v[166:169], v[36:39]
	v_mfma_f32_16x16x32_bf16 v[28:31], v[200:203], v[166:169], v[28:31]
	v_mfma_f32_16x16x32_bf16 v[20:23], v[190:193], v[174:177], v[20:23]
	v_mfma_f32_16x16x32_bf16 v[12:15], v[200:203], v[174:177], v[12:15]
	v_mfma_f32_16x16x32_bf16 v[4:7], v[190:193], v[182:185], v[4:7]
	v_mfma_f32_16x16x32_bf16 v[0:3], v[200:203], v[182:185], v[0:3]
	v_mfma_f32_16x16x32_bf16 v[52:55], v[196:199], v[162:165], v[52:55]
	v_mfma_f32_16x16x32_bf16 v[44:47], v[204:207], v[162:165], v[44:47]
	v_mfma_f32_16x16x32_bf16 v[36:39], v[196:199], v[170:173], v[36:39]
	v_mfma_f32_16x16x32_bf16 v[28:31], v[204:207], v[170:173], v[28:31]
	v_mfma_f32_16x16x32_bf16 v[20:23], v[196:199], v[178:181], v[20:23]
	v_mfma_f32_16x16x32_bf16 v[12:15], v[204:207], v[178:181], v[12:15]
	v_mfma_f32_16x16x32_bf16 v[4:7], v[196:199], v[186:189], v[4:7]
	v_mfma_f32_16x16x32_bf16 v[0:3], v[204:207], v[186:189], v[0:3]
	s_add_i32 s0, 0, 0x18000
	v_add_u32_e32 v140, s0, v155
	s_barrier
	ds_read_b128 v[128:131], v140
	ds_read_b128 v[132:135], v140 offset:1024
	ds_read_b128 v[136:139], v140 offset:2048
	ds_read_b128 v[140:143], v140 offset:3072
	s_add_u32 s50, s50, 0x100000
	s_addc_u32 s51, s51, 0
	s_mov_b32 m0, s60
	v_lshl_add_u64 v[190:191], s[50:51], 0, v[144:145]
	ds_read_b128 v[158:161], v157 offset:32768
	ds_read_b128 v[162:165], v157 offset:33792
	ds_read_b128 v[166:169], v157 offset:34816
	ds_read_b128 v[170:173], v157 offset:35840
	ds_read_b128 v[174:177], v157 offset:36864
	ds_read_b128 v[178:181], v157 offset:37888
	ds_read_b128 v[182:185], v157 offset:38912
	ds_read_b128 v[186:189], v157 offset:39936
	global_load_lds_dwordx4 v[190:191], off
	v_lshl_add_u64 v[190:191], s[50:51], 0, v[148:149]
	s_mov_b32 m0, s61
	s_nop 0
	global_load_lds_dwordx4 v[190:191], off
	s_waitcnt lgkmcnt(8)
	s_barrier
	s_waitcnt lgkmcnt(0)
	s_waitcnt lgkmcnt(0)
	v_mfma_f32_16x16x32_bf16 v[124:127], v[128:131], v[158:161], v[124:127]
	v_mfma_f32_16x16x32_bf16 v[120:123], v[136:139], v[158:161], v[120:123]
	v_mfma_f32_16x16x32_bf16 v[116:119], v[128:131], v[166:169], v[116:119]
	v_mfma_f32_16x16x32_bf16 v[112:115], v[136:139], v[166:169], v[112:115]
	v_mfma_f32_16x16x32_bf16 v[108:111], v[128:131], v[174:177], v[108:111]
	v_mfma_f32_16x16x32_bf16 v[100:103], v[136:139], v[174:177], v[100:103]
	v_mfma_f32_16x16x32_bf16 v[76:79], v[128:131], v[182:185], v[76:79]
	v_mfma_f32_16x16x32_bf16 v[72:75], v[136:139], v[182:185], v[72:75]
	v_mfma_f32_16x16x32_bf16 v[124:127], v[132:135], v[162:165], v[124:127]
	v_mfma_f32_16x16x32_bf16 v[120:123], v[140:143], v[162:165], v[120:123]
	v_mfma_f32_16x16x32_bf16 v[116:119], v[132:135], v[170:173], v[116:119]
	v_mfma_f32_16x16x32_bf16 v[112:115], v[140:143], v[170:173], v[112:115]
	v_mfma_f32_16x16x32_bf16 v[108:111], v[132:135], v[178:181], v[108:111]
	v_mfma_f32_16x16x32_bf16 v[100:103], v[140:143], v[178:181], v[100:103]
	v_mfma_f32_16x16x32_bf16 v[76:79], v[132:135], v[186:189], v[76:79]
	v_mfma_f32_16x16x32_bf16 v[72:75], v[140:143], v[186:189], v[72:75]
	s_barrier
	s_add_i32 s54, 0, 0x1c000
	s_add_i32 s0, s0, s58
	v_add_u32_e32 v204, s54, v155
	v_lshl_add_u64 v[152:153], v[152:153], 0, s[6:7]
	s_mov_b32 m0, s0
	ds_read_b128 v[190:193], v204
	ds_read_b128 v[196:199], v204 offset:1024
	ds_read_b128 v[200:203], v204 offset:2048
	ds_read_b128 v[204:207], v204 offset:3072
	global_load_lds_dwordx4 v[152:153], off
	v_lshl_add_u64 v[152:153], v[208:209], 0, s[6:7]
	s_add_i32 m0, s0, 0x2000
	s_nop 0
	global_load_lds_dwordx4 v[152:153], off
	s_barrier
	s_waitcnt lgkmcnt(0)
	s_waitcnt lgkmcnt(0)
	v_mfma_f32_16x16x32_bf16 v[104:107], v[190:193], v[158:161], v[104:107]
	v_mfma_f32_16x16x32_bf16 v[96:99], v[200:203], v[158:161], v[96:99]
	v_mfma_f32_16x16x32_bf16 v[92:95], v[190:193], v[166:169], v[92:95]
	v_mfma_f32_16x16x32_bf16 v[88:91], v[200:203], v[166:169], v[88:91]
	v_mfma_f32_16x16x32_bf16 v[84:87], v[190:193], v[174:177], v[84:87]
	v_mfma_f32_16x16x32_bf16 v[80:83], v[200:203], v[174:177], v[80:83]
	v_mfma_f32_16x16x32_bf16 v[68:71], v[190:193], v[182:185], v[68:71]
	v_mfma_f32_16x16x32_bf16 v[64:67], v[200:203], v[182:185], v[64:67]
	v_mfma_f32_16x16x32_bf16 v[104:107], v[196:199], v[162:165], v[104:107]
	v_mfma_f32_16x16x32_bf16 v[96:99], v[204:207], v[162:165], v[96:99]
	v_mfma_f32_16x16x32_bf16 v[92:95], v[196:199], v[170:173], v[92:95]
	v_mfma_f32_16x16x32_bf16 v[88:91], v[204:207], v[170:173], v[88:91]
	v_mfma_f32_16x16x32_bf16 v[84:87], v[196:199], v[178:181], v[84:87]
	v_mfma_f32_16x16x32_bf16 v[80:83], v[204:207], v[178:181], v[80:83]
	v_mfma_f32_16x16x32_bf16 v[68:71], v[196:199], v[186:189], v[68:71]
	v_mfma_f32_16x16x32_bf16 v[64:67], v[204:207], v[186:189], v[64:67]
	s_mov_b32 m0, s64
	v_lshl_add_u64 v[152:153], v[210:211], 0, s[6:7]
	s_barrier
	ds_read_b128 v[158:161], v157 offset:49152
	ds_read_b128 v[162:165], v157 offset:50176
	ds_read_b128 v[166:169], v157 offset:51200
	ds_read_b128 v[170:173], v157 offset:52224
	ds_read_b128 v[174:177], v157 offset:53248
	ds_read_b128 v[178:181], v157 offset:54272
	ds_read_b128 v[182:185], v157 offset:55296
	ds_read_b128 v[186:189], v157 offset:56320
	global_load_lds_dwordx4 v[152:153], off
	v_lshl_add_u64 v[152:153], v[212:213], 0, s[6:7]
	s_mov_b32 m0, s65
	s_nop 0
	global_load_lds_dwordx4 v[152:153], off
	s_barrier
	s_waitcnt lgkmcnt(0)
	s_waitcnt lgkmcnt(0)
	v_mfma_f32_16x16x32_bf16 v[60:63], v[128:131], v[158:161], v[60:63]
	v_mfma_f32_16x16x32_bf16 v[56:59], v[136:139], v[158:161], v[56:59]
	v_mfma_f32_16x16x32_bf16 v[48:51], v[128:131], v[166:169], v[48:51]
	v_mfma_f32_16x16x32_bf16 v[40:43], v[136:139], v[166:169], v[40:43]
	v_mfma_f32_16x16x32_bf16 v[32:35], v[128:131], v[174:177], v[32:35]
	v_mfma_f32_16x16x32_bf16 v[24:27], v[136:139], v[174:177], v[24:27]
	v_mfma_f32_16x16x32_bf16 v[16:19], v[128:131], v[182:185], v[16:19]
	v_mfma_f32_16x16x32_bf16 v[8:11], v[136:139], v[182:185], v[8:11]
	v_mfma_f32_16x16x32_bf16 v[60:63], v[132:135], v[162:165], v[60:63]
	v_mfma_f32_16x16x32_bf16 v[56:59], v[140:143], v[162:165], v[56:59]
	v_mfma_f32_16x16x32_bf16 v[48:51], v[132:135], v[170:173], v[48:51]
	v_mfma_f32_16x16x32_bf16 v[40:43], v[140:143], v[170:173], v[40:43]
	v_mfma_f32_16x16x32_bf16 v[32:35], v[132:135], v[178:181], v[32:35]
	v_mfma_f32_16x16x32_bf16 v[24:27], v[140:143], v[178:181], v[24:27]
	v_mfma_f32_16x16x32_bf16 v[16:19], v[132:135], v[186:189], v[16:19]
	v_mfma_f32_16x16x32_bf16 v[8:11], v[140:143], v[186:189], v[8:11]
	s_barrier
	s_add_u32 s50, s52, 0x100080
	s_addc_u32 s51, s53, 0
	s_add_i32 s0, s54, s58
	v_lshl_add_u64 v[128:129], s[50:51], 0, v[146:147]
	s_mov_b32 m0, s0
	s_nop 0
	global_load_lds_dwordx4 v[128:129], off
	v_lshl_add_u64 v[128:129], s[50:51], 0, v[150:151]
	s_add_i32 m0, s0, 0x2000
	s_nop 0
	global_load_lds_dwordx4 v[128:129], off
	s_waitcnt vmcnt(6)
	s_barrier
	v_mfma_f32_16x16x32_bf16 v[52:55], v[190:193], v[158:161], v[52:55]
	v_mfma_f32_16x16x32_bf16 v[44:47], v[200:203], v[158:161], v[44:47]
	v_mfma_f32_16x16x32_bf16 v[36:39], v[190:193], v[166:169], v[36:39]
	v_mfma_f32_16x16x32_bf16 v[28:31], v[200:203], v[166:169], v[28:31]
	v_mfma_f32_16x16x32_bf16 v[20:23], v[190:193], v[174:177], v[20:23]
	v_mfma_f32_16x16x32_bf16 v[12:15], v[200:203], v[174:177], v[12:15]
	v_mfma_f32_16x16x32_bf16 v[4:7], v[190:193], v[182:185], v[4:7]
	v_mfma_f32_16x16x32_bf16 v[0:3], v[200:203], v[182:185], v[0:3]
	v_mfma_f32_16x16x32_bf16 v[52:55], v[196:199], v[162:165], v[52:55]
	v_mfma_f32_16x16x32_bf16 v[44:47], v[204:207], v[162:165], v[44:47]
	v_mfma_f32_16x16x32_bf16 v[36:39], v[196:199], v[170:173], v[36:39]
	v_mfma_f32_16x16x32_bf16 v[28:31], v[204:207], v[170:173], v[28:31]
	v_mfma_f32_16x16x32_bf16 v[20:23], v[196:199], v[178:181], v[20:23]
	v_mfma_f32_16x16x32_bf16 v[12:15], v[204:207], v[178:181], v[12:15]
	v_mfma_f32_16x16x32_bf16 v[4:7], v[196:199], v[186:189], v[4:7]
	v_mfma_f32_16x16x32_bf16 v[0:3], v[204:207], v[186:189], v[0:3]
	s_add_u32 s48, s48, 0x100
	s_addc_u32 s49, s49, 0
	s_cmp_ge_i32 s79, s76
	s_barrier
	s_cbranch_scc1 .LBB0_1253
